# one static priority raise (s_setprio 1) for the second co-resident block (bid >= 256) inside the q and in-proj tile main loops
# baseline (speedup 1.0000x reference)
; DI int TID() { int t = threadIdx.x; asm volatile("" : "+v"(t)); return t; }
; template <bool SWAP, int MI, class AF, class BF, class EF>
; DI void gemm_tile(const AF& af, const BF& bfn, const EF& ef, int m0, int n0, int K, char* smem) {
;   constexpr int AROWS = MI * 64;
;   u16* As = (u16*)smem;
;   u16* Bs = As + 2 * AROWS * 40;
;   const int tid = TID(), lane = tid & 63, w = tid >> 6;
;   const int wm = w >> 1, wn = w & 1, l32 = lane & 31, h = lane >> 5;
;   const int lrow = (tid >> 6) * 16 + ((tid >> 5) & 1) * 8 + ((tid >> 2) & 1) * 4 + ((tid >> 3) & 3), lk = (tid & 3) * 8;
;   f32x16 acc[MI][2];
; #pragma unroll
;   for (int i = 0; i < MI; ++i)
; #pragma unroll
;     for (int j = 0; j < 2; ++j)
; #pragma unroll
;       for (int r = 0; r < 16; ++r) acc[i][j][r] = 0.f;
;   u32x4 ra[MI], rb[2];
;   const int nk = K >> 5;
; #pragma unroll
;   for (int i = 0; i < MI; ++i) ra[i] = *(const u32x4*)af(m0 + lrow + 64 * i, lk);
; #pragma unroll
;   for (int i = 0; i < 2; ++i) rb[i] = *(const u32x4*)bfn(n0 + lrow + 64 * i, lk);
; #pragma unroll
;   for (int i = 0; i < MI; ++i) *(u32x4*)&As[(lrow + 64 * i) * 40 + lk] = ra[i];
; #pragma unroll
;   for (int i = 0; i < 2; ++i) *(u32x4*)&Bs[(lrow + 64 * i) * 40 + lk] = rb[i];
;   {
;     const int k1 = (nk > 1) ? 32 + lk : lk;
; #pragma unroll
;     for (int i = 0; i < MI; ++i) ra[i] = *(const u32x4*)af(m0 + lrow + 64 * i, k1);
; #pragma unroll
;     for (int i = 0; i < 2; ++i) rb[i] = *(const u32x4*)bfn(n0 + lrow + 64 * i, k1);
;   }
;   __syncthreads();
; DI void phase_inproj(const Params& p, int l, int bid, int nblk, char* smem) {
;     ...
;     if (nt >= 18 && nt < 22) gemm_tile<false, 4>(af, bfn, efN, mt * 256, nt * 128, 1024, smem);
;     else gemm_tile<true, 4>(af, bfn, efT, mt * 256, nt * 128, 1024, smem);
.LBB0_423:
	s_sub_i32 s0, s35, 18
	s_lshl_b32 s73, s34, 8
	s_lshl_b32 s72, s35, 7
	s_cmp_gt_u32 s0, 3
	s_mov_b64 s[0:1], -1
	s_cbranch_scc0 .LBB0_747
	s_cmpk_eq_u32 s72, 0xb00
	s_cbranch_scc1 .Lip_orig
	v_readlane_b32 s56, v253, 0
	s_nop 0
	s_lshr_b32 s56, s56, 8
	s_cmp_lg_u32 s56, 0
	s_cbranch_scc0 .Lgemm_ipt_np
	s_setprio 1
.Lgemm_ipt_np:
	v_lshrrev_b32_e32 v128, 6, v218
	v_bfe_u32 v129, v218, 5, 1
	v_bfe_u32 v130, v218, 2, 1
	v_bfe_u32 v131, v218, 3, 2
	v_lshlrev_b32_e32 v132, 4, v128
	v_lshl_add_u32 v132, v129, 3, v132
	v_lshl_add_u32 v132, v130, 2, v132
	v_add_u32_e32 v132, v132, v131
	v_and_b32_e32 v133, 3, v218
	v_lshlrev_b32_e32 v133, 4, v133
	v_lshl_add_u32 v200, v132, 11, v133
	v_mul_u32_u24_e32 v134, 80, v132
	v_add_u32_e32 v202, v134, v133
	v_and_b32_e32 v135, 31, v218
	v_lshrrev_b32_e32 v136, 7, v218
	v_bfe_u32 v137, v218, 6, 1
	v_lshl_add_u32 v136, v136, 7, v135
	v_lshl_add_u32 v137, v137, 6, v135
	v_mul_u32_u24_e32 v136, 80, v136
	v_mul_u32_u24_e32 v137, 80, v137
	v_lshl_add_u32 v206, v129, 4, v136
	v_lshl_add_u32 v207, v129, 4, v137
	s_add_i32 s56, s73, 0
	s_lshl_b32 s56, s56, 11
	s_add_u32 s26, s6, s56
	s_addc_u32 s27, s7, 0
	s_add_i32 s56, s73, 64
	s_lshl_b32 s56, s56, 11
	s_add_u32 s28, s6, s56
	s_addc_u32 s29, s7, 0
	s_add_i32 s56, s73, 128
	s_lshl_b32 s56, s56, 11
	s_add_u32 s30, s6, s56
	s_addc_u32 s31, s7, 0
	s_add_i32 s56, s73, 192
	s_lshl_b32 s56, s56, 11
	s_add_u32 s36, s6, s56
	s_addc_u32 s37, s7, 0
	s_add_i32 s56, s72, 0
	s_lshl_b32 s56, s56, 11
	s_add_u32 s42, s50, s56
	s_addc_u32 s43, s51, 0
	s_add_i32 s56, s72, 64
	s_lshl_b32 s56, s56, 11
	s_add_u32 s48, s50, s56
	s_addc_u32 s49, s51, 0
	v_mov_b64_e32 v[0:1], 0
	v_mov_b64_e32 v[2:3], 0
	v_mov_b64_e32 v[4:5], 0
	v_mov_b64_e32 v[6:7], 0
	v_mov_b64_e32 v[8:9], 0
	v_mov_b64_e32 v[10:11], 0
	v_mov_b64_e32 v[12:13], 0
	v_mov_b64_e32 v[14:15], 0
	v_mov_b64_e32 v[16:17], 0
	v_mov_b64_e32 v[18:19], 0
	v_mov_b64_e32 v[20:21], 0
	v_mov_b64_e32 v[22:23], 0
	v_mov_b64_e32 v[24:25], 0
	v_mov_b64_e32 v[26:27], 0
	v_mov_b64_e32 v[28:29], 0
	v_mov_b64_e32 v[30:31], 0
	v_mov_b64_e32 v[32:33], 0
	v_mov_b64_e32 v[34:35], 0
	v_mov_b64_e32 v[36:37], 0
	v_mov_b64_e32 v[38:39], 0
	v_mov_b64_e32 v[40:41], 0
	v_mov_b64_e32 v[42:43], 0
	v_mov_b64_e32 v[44:45], 0
	v_mov_b64_e32 v[46:47], 0
	v_mov_b64_e32 v[48:49], 0
	v_mov_b64_e32 v[50:51], 0
	v_mov_b64_e32 v[52:53], 0
	v_mov_b64_e32 v[54:55], 0
	v_mov_b64_e32 v[56:57], 0
	v_mov_b64_e32 v[58:59], 0
	v_mov_b64_e32 v[60:61], 0
	v_mov_b64_e32 v[62:63], 0
	v_mov_b64_e32 v[64:65], 0
	v_mov_b64_e32 v[66:67], 0
	v_mov_b64_e32 v[68:69], 0
	v_mov_b64_e32 v[70:71], 0
	v_mov_b64_e32 v[72:73], 0
	v_mov_b64_e32 v[74:75], 0
	v_mov_b64_e32 v[76:77], 0
	v_mov_b64_e32 v[78:79], 0
	v_mov_b64_e32 v[80:81], 0
	v_mov_b64_e32 v[82:83], 0
	v_mov_b64_e32 v[84:85], 0
	v_mov_b64_e32 v[86:87], 0
	v_mov_b64_e32 v[88:89], 0
	v_mov_b64_e32 v[90:91], 0
	v_mov_b64_e32 v[92:93], 0
	v_mov_b64_e32 v[94:95], 0
	v_mov_b64_e32 v[96:97], 0
	v_mov_b64_e32 v[98:99], 0
	v_mov_b64_e32 v[100:101], 0
	v_mov_b64_e32 v[102:103], 0
	v_mov_b64_e32 v[104:105], 0
	v_mov_b64_e32 v[106:107], 0
	v_mov_b64_e32 v[108:109], 0
	v_mov_b64_e32 v[110:111], 0
	v_mov_b64_e32 v[112:113], 0
	v_mov_b64_e32 v[114:115], 0
	v_mov_b64_e32 v[116:117], 0
	v_mov_b64_e32 v[118:119], 0
	v_mov_b64_e32 v[120:121], 0
	v_mov_b64_e32 v[122:123], 0
	v_mov_b64_e32 v[124:125], 0
	v_mov_b64_e32 v[126:127], 0
	s_mov_b32 s64, 0
	v_add_u32_e32 v201, s64, v200
	global_load_dwordx4 v[128:131], v201, s[26:27]
	global_load_dwordx4 v[152:155], v201, s[26:27] offset:64
	global_load_dwordx4 v[132:135], v201, s[28:29]
	global_load_dwordx4 v[156:159], v201, s[28:29] offset:64
	global_load_dwordx4 v[136:139], v201, s[30:31]
	global_load_dwordx4 v[160:163], v201, s[30:31] offset:64
	global_load_dwordx4 v[140:143], v201, s[36:37]
	global_load_dwordx4 v[164:167], v201, s[36:37] offset:64
	global_load_dwordx4 v[144:147], v201, s[42:43]
	global_load_dwordx4 v[168:171], v201, s[42:43] offset:64
	global_load_dwordx4 v[148:151], v201, s[48:49]
	global_load_dwordx4 v[176:179], v201, s[48:49] offset:64
	s_add_i32 s64, s64, 0x80
	s_movk_i32 s65, 16
	s_waitcnt vmcnt(0)
	ds_write_b128 v202, v[128:131] offset:0
	ds_write_b128 v202, v[132:135] offset:5120
	ds_write_b128 v202, v[136:139] offset:10240
	ds_write_b128 v202, v[140:143] offset:15360
	ds_write_b128 v202, v[144:147] offset:40960
	ds_write_b128 v202, v[148:151] offset:46080
	s_waitcnt lgkmcnt(0)
	s_barrier
	ds_read_b128 v[196:199], v207 offset:40960
	ds_read_b128 v[228:231], v207 offset:43520
	ds_read_b128 v[180:183], v206 offset:0
	ds_read_b128 v[184:187], v206 offset:2560
	ds_read_b128 v[188:191], v206 offset:5120
	ds_read_b128 v[192:195], v206 offset:7680
; template <bool SWAP, int MI, class AF, class BF, class EF>
; DI void gemm_tile(const AF& af, const BF& bfn, const EF& ef, int m0, int n0, int K, char* smem) {
;     ...
;   for (int kt = 0; kt < nk; ++kt) {
;     const int cur = kt & 1;
;     const u16* Ab = As + cur * AROWS * 40;
;     const u16* Bb = Bs + cur * 128 * 40;
; #pragma unroll
;     for (int ks = 0; ks < 2; ++ks) {
;       bf16x8 a[MI], b[2];
; #pragma unroll
;       for (int i = 0; i < MI; ++i) a[i] = *(const bf16x8*)&Ab[(wm * (MI * 32) + i * 32 + l32) * 40 + ks * 16 + h * 8];
; #pragma unroll
;       for (int i = 0; i < 2; ++i) b[i] = *(const bf16x8*)&Bb[(wn * 64 + i * 32 + l32) * 40 + ks * 16 + h * 8];
; #pragma unroll
;       for (int i = 0; i < MI; ++i)
; #pragma unroll
;         for (int j = 0; j < 2; ++j)
;           acc[i][j] = SWAP ? __builtin_amdgcn_mfma_f32_32x32x16_bf16(b[j], a[i], acc[i][j], 0, 0, 0)
;                            : __builtin_amdgcn_mfma_f32_32x32x16_bf16(a[i], b[j], acc[i][j], 0, 0, 0);
;     }
;     {
;       u16* An = As + (cur ^ 1) * AROWS * 40;
;       u16* Bn = Bs + (cur ^ 1) * 128 * 40;
; #pragma unroll
;       for (int i = 0; i < MI; ++i) *(u32x4*)&An[(lrow + 64 * i) * 40 + lk] = ra[i];
; #pragma unroll
;       for (int i = 0; i < 2; ++i) *(u32x4*)&Bn[(lrow + 64 * i) * 40 + lk] = rb[i];
;       const int kn = (kt + 2 < nk) ? kt + 2 : nk - 1;
;       const int k0 = kn * 32 + lk;
; #pragma unroll
;       for (int i = 0; i < MI; ++i) ra[i] = *(const u32x4*)af(m0 + lrow + 64 * i, k0);
; #pragma unroll
;       for (int i = 0; i < 2; ++i) rb[i] = *(const u32x4*)bfn(n0 + lrow + 64 * i, k0);
;     }
;     __syncthreads();
;   }
.Lgemm_ipt_loop:
	ds_read_b128 v[232:235], v207 offset:40992
	ds_read_b128 v[236:239], v207 offset:43552
	ds_read_b128 v[220:223], v206 offset:32
	ds_read_b128 v[240:243], v206 offset:2592
	ds_read_b128 v[244:247], v206 offset:5152
	ds_read_b128 v[248:251], v206 offset:7712
	s_waitcnt lgkmcnt(9)
	v_mfma_f32_32x32x16_bf16 v[112:127], v[196:199], v[180:183], v[112:127]
	v_mfma_f32_32x32x16_bf16 v[96:111], v[228:231], v[180:183], v[96:111]
	s_waitcnt lgkmcnt(8)
	v_mfma_f32_32x32x16_bf16 v[80:95], v[196:199], v[184:187], v[80:95]
	v_mfma_f32_32x32x16_bf16 v[64:79], v[228:231], v[184:187], v[64:79]
	ds_write_b128 v202, v[152:155] offset:20480
	ds_write_b128 v202, v[156:159] offset:25600
	ds_write_b128 v202, v[160:163] offset:30720
	ds_write_b128 v202, v[164:167] offset:35840
	ds_write_b128 v202, v[168:171] offset:51200
	ds_write_b128 v202, v[176:179] offset:56320
	v_add_u32_e32 v201, s64, v200
	global_load_dwordx4 v[128:131], v201, s[26:27]
	global_load_dwordx4 v[152:155], v201, s[26:27] offset:64
	global_load_dwordx4 v[132:135], v201, s[28:29]
	global_load_dwordx4 v[156:159], v201, s[28:29] offset:64
	global_load_dwordx4 v[136:139], v201, s[30:31]
	global_load_dwordx4 v[160:163], v201, s[30:31] offset:64
	global_load_dwordx4 v[140:143], v201, s[36:37]
	global_load_dwordx4 v[164:167], v201, s[36:37] offset:64
	global_load_dwordx4 v[144:147], v201, s[42:43]
	global_load_dwordx4 v[168:171], v201, s[42:43] offset:64
	global_load_dwordx4 v[148:151], v201, s[48:49]
	global_load_dwordx4 v[176:179], v201, s[48:49] offset:64
	s_add_i32 s64, s64, 0x80
	s_min_u32 s64, s64, 0x780
	s_waitcnt lgkmcnt(13)
	v_mfma_f32_32x32x16_bf16 v[48:63], v[196:199], v[188:191], v[48:63]
	v_mfma_f32_32x32x16_bf16 v[32:47], v[228:231], v[188:191], v[32:47]
	s_waitcnt lgkmcnt(12)
	v_mfma_f32_32x32x16_bf16 v[16:31], v[196:199], v[192:195], v[16:31]
	v_mfma_f32_32x32x16_bf16 v[0:15], v[228:231], v[192:195], v[0:15]
	s_waitcnt lgkmcnt(0)
	s_barrier
	ds_read_b128 v[196:199], v207 offset:51200
	ds_read_b128 v[228:231], v207 offset:53760
	ds_read_b128 v[180:183], v206 offset:20480
	ds_read_b128 v[184:187], v206 offset:23040
	ds_read_b128 v[188:191], v206 offset:25600
	ds_read_b128 v[192:195], v206 offset:28160
	v_mfma_f32_32x32x16_bf16 v[112:127], v[232:235], v[220:223], v[112:127]
	v_mfma_f32_32x32x16_bf16 v[96:111], v[236:239], v[220:223], v[96:111]
	v_mfma_f32_32x32x16_bf16 v[80:95], v[232:235], v[240:243], v[80:95]
	v_mfma_f32_32x32x16_bf16 v[64:79], v[236:239], v[240:243], v[64:79]
	v_mfma_f32_32x32x16_bf16 v[48:63], v[232:235], v[244:247], v[48:63]
	v_mfma_f32_32x32x16_bf16 v[32:47], v[236:239], v[244:247], v[32:47]
	v_mfma_f32_32x32x16_bf16 v[16:31], v[232:235], v[248:251], v[16:31]
	v_mfma_f32_32x32x16_bf16 v[0:15], v[236:239], v[248:251], v[0:15]
	ds_read_b128 v[232:235], v207 offset:51232
	ds_read_b128 v[236:239], v207 offset:53792
	ds_read_b128 v[220:223], v206 offset:20512
	ds_read_b128 v[240:243], v206 offset:23072
	ds_read_b128 v[244:247], v206 offset:25632
	ds_read_b128 v[248:251], v206 offset:28192
	s_waitcnt lgkmcnt(9)
	v_mfma_f32_32x32x16_bf16 v[112:127], v[196:199], v[180:183], v[112:127]
	v_mfma_f32_32x32x16_bf16 v[96:111], v[228:231], v[180:183], v[96:111]
	s_waitcnt lgkmcnt(8)
	v_mfma_f32_32x32x16_bf16 v[80:95], v[196:199], v[184:187], v[80:95]
	v_mfma_f32_32x32x16_bf16 v[64:79], v[228:231], v[184:187], v[64:79]
	s_waitcnt vmcnt(0)
	ds_write_b128 v202, v[128:131] offset:0
	ds_write_b128 v202, v[132:135] offset:5120
	ds_write_b128 v202, v[136:139] offset:10240
	ds_write_b128 v202, v[140:143] offset:15360
	ds_write_b128 v202, v[144:147] offset:40960
	ds_write_b128 v202, v[148:151] offset:46080
	s_waitcnt lgkmcnt(13)
	v_mfma_f32_32x32x16_bf16 v[48:63], v[196:199], v[188:191], v[48:63]
	v_mfma_f32_32x32x16_bf16 v[32:47], v[228:231], v[188:191], v[32:47]
	s_waitcnt lgkmcnt(12)
	v_mfma_f32_32x32x16_bf16 v[16:31], v[196:199], v[192:195], v[16:31]
	v_mfma_f32_32x32x16_bf16 v[0:15], v[228:231], v[192:195], v[0:15]
	s_waitcnt lgkmcnt(0)
	s_barrier
	ds_read_b128 v[196:199], v207 offset:40960
	ds_read_b128 v[228:231], v207 offset:43520
	ds_read_b128 v[180:183], v206 offset:0
	ds_read_b128 v[184:187], v206 offset:2560
	ds_read_b128 v[188:191], v206 offset:5120
	ds_read_b128 v[192:195], v206 offset:7680
	v_mfma_f32_32x32x16_bf16 v[112:127], v[232:235], v[220:223], v[112:127]
	v_mfma_f32_32x32x16_bf16 v[96:111], v[236:239], v[220:223], v[96:111]
	v_mfma_f32_32x32x16_bf16 v[80:95], v[232:235], v[240:243], v[80:95]
	v_mfma_f32_32x32x16_bf16 v[64:79], v[236:239], v[240:243], v[64:79]
	v_mfma_f32_32x32x16_bf16 v[48:63], v[232:235], v[244:247], v[48:63]
	v_mfma_f32_32x32x16_bf16 v[32:47], v[236:239], v[244:247], v[32:47]
	v_mfma_f32_32x32x16_bf16 v[16:31], v[232:235], v[248:251], v[16:31]
	v_mfma_f32_32x32x16_bf16 v[0:15], v[236:239], v[248:251], v[0:15]
	s_add_i32 s65, s65, -1
	s_cmp_lg_u32 s65, 0
	s_cbranch_scc1 .Lgemm_ipt_loop
; DI u32 pack2(float a, float b) { return (u32)f2bf(a) | ((u32)f2bf(b) << 16); }
; template <bool SWAP, int MI, class AF, class BF, class EF>
; DI void gemm_tile(const AF& af, const BF& bfn, const EF& ef, int m0, int n0, int K, char* smem) {
;     ...
; #pragma unroll
;   for (int i = 0; i < MI; ++i)
; #pragma unroll
;     for (int j = 0; j < 2; ++j)
; #pragma unroll
;       for (int rg = 0; rg < 4; ++rg) {
;         const int m = SWAP ? (m0 + wm * (MI * 32) + i * 32 + l32) : (m0 + wm * (MI * 32) + i * 32 + rg * 8 + h * 4);
;         const int n = SWAP ? (n0 + wn * 64 + j * 32 + rg * 8 + h * 4) : (n0 + wn * 64 + j * 32 + l32);
;         ef(m, n, acc[i][j][rg * 4 + 0], acc[i][j][rg * 4 + 1], acc[i][j][rg * 4 + 2], acc[i][j][rg * 4 + 3]);
;       }
; DI void phase_inproj(const Params& p, int l, int bid, int nblk, char* smem) {
;     ...
;   auto efT = [=](int m, int n, float v0, float v1, float v2, float v3) {
;     const uint2 o = {pack2(v0, v1), pack2(v2, v3)};
;     if (n < 768) *(uint2*)&PHY[(size_t)m * 768 + n] = o;
;     else if (n < 1280) *(uint2*)&PZ[(size_t)m * 512 + (n - 768)] = o;
;     else if (n < 2304) *(uint2*)&PXBC[(size_t)m * 1024 + (n - 1280)] = o;
;     else if (n >= 2816 && n < 2832) { float4 f = {v0, v1, v2, v3}; *(float4*)&DT[(size_t)m * 16 + (n - 2816)] = f; }
;   };
	s_waitcnt lgkmcnt(0)
	s_setprio 0
	s_waitcnt vmcnt(0)
	v_and_b32_e32 v128, 31, v218
	v_lshrrev_b32_e32 v129, 7, v218
	v_bfe_u32 v130, v218, 5, 1
	v_bfe_u32 v131, v218, 6, 1
	v_lshl_add_u32 v128, v129, 7, v128
	v_mul_u32_u24_e32 v128, 272, v128
	v_lshlrev_b32_e32 v131, 7, v131
	v_lshl_add_u32 v131, v130, 3, v131
	v_add_u32_e32 v128, v128, v131
	s_nop 7
	v_cvt_pk_bf16_f32 v112, v112, v113
	v_cvt_pk_bf16_f32 v113, v114, v115
	v_cvt_pk_bf16_f32 v116, v116, v117
	v_cvt_pk_bf16_f32 v117, v118, v119
	v_cvt_pk_bf16_f32 v120, v120, v121
	v_cvt_pk_bf16_f32 v121, v122, v123
	v_cvt_pk_bf16_f32 v124, v124, v125
	v_cvt_pk_bf16_f32 v125, v126, v127
	ds_write_b64 v128, v[112:113] offset:0
	ds_write_b64 v128, v[116:117] offset:16
	ds_write_b64 v128, v[120:121] offset:32
	ds_write_b64 v128, v[124:125] offset:48
	v_cvt_pk_bf16_f32 v96, v96, v97
	v_cvt_pk_bf16_f32 v97, v98, v99
	v_cvt_pk_bf16_f32 v100, v100, v101
	v_cvt_pk_bf16_f32 v101, v102, v103
	v_cvt_pk_bf16_f32 v104, v104, v105
	v_cvt_pk_bf16_f32 v105, v106, v107
	v_cvt_pk_bf16_f32 v108, v108, v109
	v_cvt_pk_bf16_f32 v109, v110, v111
	ds_write_b64 v128, v[96:97] offset:64
	ds_write_b64 v128, v[100:101] offset:80
	ds_write_b64 v128, v[104:105] offset:96
	ds_write_b64 v128, v[108:109] offset:112
	v_cvt_pk_bf16_f32 v80, v80, v81
	v_cvt_pk_bf16_f32 v81, v82, v83
	v_cvt_pk_bf16_f32 v84, v84, v85
	v_cvt_pk_bf16_f32 v85, v86, v87
	v_cvt_pk_bf16_f32 v88, v88, v89
	v_cvt_pk_bf16_f32 v89, v90, v91
	v_cvt_pk_bf16_f32 v92, v92, v93
	v_cvt_pk_bf16_f32 v93, v94, v95
	ds_write_b64 v128, v[80:81] offset:8704
	ds_write_b64 v128, v[84:85] offset:8720
	ds_write_b64 v128, v[88:89] offset:8736
	ds_write_b64 v128, v[92:93] offset:8752
	v_cvt_pk_bf16_f32 v64, v64, v65
	v_cvt_pk_bf16_f32 v65, v66, v67
	v_cvt_pk_bf16_f32 v68, v68, v69
	v_cvt_pk_bf16_f32 v69, v70, v71
	v_cvt_pk_bf16_f32 v72, v72, v73
	v_cvt_pk_bf16_f32 v73, v74, v75
	v_cvt_pk_bf16_f32 v76, v76, v77
	v_cvt_pk_bf16_f32 v77, v78, v79
	ds_write_b64 v128, v[64:65] offset:8768
	ds_write_b64 v128, v[68:69] offset:8784
	ds_write_b64 v128, v[72:73] offset:8800
	ds_write_b64 v128, v[76:77] offset:8816
	v_cvt_pk_bf16_f32 v48, v48, v49
	v_cvt_pk_bf16_f32 v49, v50, v51
	v_cvt_pk_bf16_f32 v52, v52, v53
	v_cvt_pk_bf16_f32 v53, v54, v55
	v_cvt_pk_bf16_f32 v56, v56, v57
	v_cvt_pk_bf16_f32 v57, v58, v59
	v_cvt_pk_bf16_f32 v60, v60, v61
	v_cvt_pk_bf16_f32 v61, v62, v63
	ds_write_b64 v128, v[48:49] offset:17408
	ds_write_b64 v128, v[52:53] offset:17424
	ds_write_b64 v128, v[56:57] offset:17440
	ds_write_b64 v128, v[60:61] offset:17456
	v_cvt_pk_bf16_f32 v32, v32, v33
	v_cvt_pk_bf16_f32 v33, v34, v35
	v_cvt_pk_bf16_f32 v36, v36, v37
	v_cvt_pk_bf16_f32 v37, v38, v39
	v_cvt_pk_bf16_f32 v40, v40, v41
	v_cvt_pk_bf16_f32 v41, v42, v43
	v_cvt_pk_bf16_f32 v44, v44, v45
	v_cvt_pk_bf16_f32 v45, v46, v47
	ds_write_b64 v128, v[32:33] offset:17472
	ds_write_b64 v128, v[36:37] offset:17488
	ds_write_b64 v128, v[40:41] offset:17504
	ds_write_b64 v128, v[44:45] offset:17520
	v_cvt_pk_bf16_f32 v16, v16, v17
	v_cvt_pk_bf16_f32 v17, v18, v19
	v_cvt_pk_bf16_f32 v20, v20, v21
	v_cvt_pk_bf16_f32 v21, v22, v23
	v_cvt_pk_bf16_f32 v24, v24, v25
	v_cvt_pk_bf16_f32 v25, v26, v27
	v_cvt_pk_bf16_f32 v28, v28, v29
	v_cvt_pk_bf16_f32 v29, v30, v31
	ds_write_b64 v128, v[16:17] offset:26112
	ds_write_b64 v128, v[20:21] offset:26128
	ds_write_b64 v128, v[24:25] offset:26144
	ds_write_b64 v128, v[28:29] offset:26160
	v_cvt_pk_bf16_f32 v0, v0, v1
	v_cvt_pk_bf16_f32 v1, v2, v3
	v_cvt_pk_bf16_f32 v4, v4, v5
	v_cvt_pk_bf16_f32 v5, v6, v7
	v_cvt_pk_bf16_f32 v8, v8, v9
	v_cvt_pk_bf16_f32 v9, v10, v11
	v_cvt_pk_bf16_f32 v12, v12, v13
	v_cvt_pk_bf16_f32 v13, v14, v15
	ds_write_b64 v128, v[0:1] offset:26176
	ds_write_b64 v128, v[4:5] offset:26192
	ds_write_b64 v128, v[8:9] offset:26208
	ds_write_b64 v128, v[12:13] offset:26224
	s_cmpk_lt_u32 s72, 0x300
	s_cbranch_scc1 .Left_phy
	s_cmpk_lt_u32 s72, 0x500
	s_cbranch_scc1 .Left_pz
	s_lshl_b32 s16, s73, 11
	s_lshl_b32 s17, s72, 1
	s_add_u32 s16, s16, s17
	s_add_u32 s16, s16, 0x59ff600
	s_movk_i32 s38, 0x800
	s_mov_b32 s39, 0x8000
	s_branch .Left_go

; DI void phase_inproj(const Params& p, int l, int bid, int nblk, char* smem) {
;     ...
;   const int nlat = (l == 1) ? 128 * 23 : (ROWS / 256) * 23;
;   const int ntile = (l == 1) ? nlat + NB * 9 : nlat;
;   const int vb = (nblk % 8 == 0) ? (bid & 7) * (nblk >> 3) + (bid >> 3) : bid;
;   for (int t = vb; t < ntile; t += nblk) {
;     int mt, nt;
;     if (t < nlat) {
;       const int mi = t / 23;
;       nt = t % 23;
;       mt = (l == 1) ? (mi >> 3) * 9 + (mi & 7) + 1 : mi;
;     } else {
;       const int u = t - nlat, q = u % 9;
;       mt = (u / 9) * 9;
;       nt = (q < 8) ? 10 + q : 22;
;     }
;     if (nt >= 18 && nt < 22) gemm_tile<false, 4>(af, bfn, efN, mt * 256, nt * 128, 1024, smem);
;     else gemm_tile<true, 4>(af, bfn, efT, mt * 256, nt * 128, 1024, smem);
.LBB0_747:
	s_and_b64 vcc, exec, s[0:1]
	s_cbranch_vccz .LBB0_416
	v_readlane_b32 s56, v253, 0
	s_nop 0
	s_lshr_b32 s56, s56, 8
	s_cmp_lg_u32 s56, 0
	s_cbranch_scc0 .Lgemm_ipn_np
	s_setprio 1

; template <bool SWAP, int MI, class AF, class BF, class EF>
; DI void gemm_tile(const AF& af, const BF& bfn, const EF& ef, int m0, int n0, int K, char* smem) {
;     ...
;   for (int kt = 0; kt < nk; ++kt) {
;     const int cur = kt & 1;
;     const u16* Ab = As + cur * AROWS * 40;
;     const u16* Bb = Bs + cur * 128 * 40;
; #pragma unroll
;     for (int ks = 0; ks < 2; ++ks) {
;       bf16x8 a[MI], b[2];
; #pragma unroll
;       for (int i = 0; i < MI; ++i) a[i] = *(const bf16x8*)&Ab[(wm * (MI * 32) + i * 32 + l32) * 40 + ks * 16 + h * 8];
; #pragma unroll
;       for (int i = 0; i < 2; ++i) b[i] = *(const bf16x8*)&Bb[(wn * 64 + i * 32 + l32) * 40 + ks * 16 + h * 8];
; #pragma unroll
;       for (int i = 0; i < MI; ++i)
; #pragma unroll
;         for (int j = 0; j < 2; ++j)
;           acc[i][j] = SWAP ? __builtin_amdgcn_mfma_f32_32x32x16_bf16(b[j], a[i], acc[i][j], 0, 0, 0)
;                            : __builtin_amdgcn_mfma_f32_32x32x16_bf16(a[i], b[j], acc[i][j], 0, 0, 0);
;     }
;     {
;       u16* An = As + (cur ^ 1) * AROWS * 40;
;       u16* Bn = Bs + (cur ^ 1) * 128 * 40;
; #pragma unroll
;       for (int i = 0; i < MI; ++i) *(u32x4*)&An[(lrow + 64 * i) * 40 + lk] = ra[i];
; #pragma unroll
;       for (int i = 0; i < 2; ++i) *(u32x4*)&Bn[(lrow + 64 * i) * 40 + lk] = rb[i];
;       const int kn = (kt + 2 < nk) ? kt + 2 : nk - 1;
;       const int k0 = kn * 32 + lk;
; #pragma unroll
;       for (int i = 0; i < MI; ++i) ra[i] = *(const u32x4*)af(m0 + lrow + 64 * i, k0);
; #pragma unroll
;       for (int i = 0; i < 2; ++i) rb[i] = *(const u32x4*)bfn(n0 + lrow + 64 * i, k0);
;     }
;     __syncthreads();
;   }
.Lgemm_ipn_loop:
	ds_read_b128 v[232:235], v207 offset:40992
	ds_read_b128 v[236:239], v207 offset:43552
	ds_read_b128 v[220:223], v206 offset:32
	ds_read_b128 v[240:243], v206 offset:2592
	ds_read_b128 v[244:247], v206 offset:5152
	ds_read_b128 v[248:251], v206 offset:7712
	s_waitcnt lgkmcnt(9)
	v_mfma_f32_32x32x16_bf16 v[112:127], v[180:183], v[196:199], v[112:127]
	v_mfma_f32_32x32x16_bf16 v[96:111], v[180:183], v[228:231], v[96:111]
	s_waitcnt lgkmcnt(8)
	v_mfma_f32_32x32x16_bf16 v[80:95], v[184:187], v[196:199], v[80:95]
	v_mfma_f32_32x32x16_bf16 v[64:79], v[184:187], v[228:231], v[64:79]
	ds_write_b128 v202, v[152:155] offset:20480
	ds_write_b128 v202, v[156:159] offset:25600
	ds_write_b128 v202, v[160:163] offset:30720
	ds_write_b128 v202, v[164:167] offset:35840
	ds_write_b128 v202, v[168:171] offset:51200
	ds_write_b128 v202, v[176:179] offset:56320
	v_add_u32_e32 v201, s64, v200
	global_load_dwordx4 v[128:131], v201, s[26:27]
	global_load_dwordx4 v[152:155], v201, s[26:27] offset:64
	global_load_dwordx4 v[132:135], v201, s[28:29]
	global_load_dwordx4 v[156:159], v201, s[28:29] offset:64
	global_load_dwordx4 v[136:139], v201, s[30:31]
	global_load_dwordx4 v[160:163], v201, s[30:31] offset:64
	global_load_dwordx4 v[140:143], v201, s[36:37]
	global_load_dwordx4 v[164:167], v201, s[36:37] offset:64
	global_load_dwordx4 v[144:147], v201, s[42:43]
	global_load_dwordx4 v[168:171], v201, s[42:43] offset:64
	global_load_dwordx4 v[148:151], v201, s[48:49]
	global_load_dwordx4 v[176:179], v201, s[48:49] offset:64
	s_add_i32 s64, s64, 0x80
	s_min_u32 s64, s64, 0x780
	s_waitcnt lgkmcnt(13)
	v_mfma_f32_32x32x16_bf16 v[48:63], v[188:191], v[196:199], v[48:63]
	v_mfma_f32_32x32x16_bf16 v[32:47], v[188:191], v[228:231], v[32:47]
	s_waitcnt lgkmcnt(12)
	v_mfma_f32_32x32x16_bf16 v[16:31], v[192:195], v[196:199], v[16:31]
	v_mfma_f32_32x32x16_bf16 v[0:15], v[192:195], v[228:231], v[0:15]
	s_waitcnt lgkmcnt(0)
	s_barrier
	ds_read_b128 v[196:199], v207 offset:51200
	ds_read_b128 v[228:231], v207 offset:53760
	ds_read_b128 v[180:183], v206 offset:20480
	ds_read_b128 v[184:187], v206 offset:23040
	ds_read_b128 v[188:191], v206 offset:25600
	ds_read_b128 v[192:195], v206 offset:28160
	v_mfma_f32_32x32x16_bf16 v[112:127], v[220:223], v[232:235], v[112:127]
	v_mfma_f32_32x32x16_bf16 v[96:111], v[220:223], v[236:239], v[96:111]
	v_mfma_f32_32x32x16_bf16 v[80:95], v[240:243], v[232:235], v[80:95]
	v_mfma_f32_32x32x16_bf16 v[64:79], v[240:243], v[236:239], v[64:79]
	v_mfma_f32_32x32x16_bf16 v[48:63], v[244:247], v[232:235], v[48:63]
	v_mfma_f32_32x32x16_bf16 v[32:47], v[244:247], v[236:239], v[32:47]
	v_mfma_f32_32x32x16_bf16 v[16:31], v[248:251], v[232:235], v[16:31]
	v_mfma_f32_32x32x16_bf16 v[0:15], v[248:251], v[236:239], v[0:15]
	ds_read_b128 v[232:235], v207 offset:51232
	ds_read_b128 v[236:239], v207 offset:53792
	ds_read_b128 v[220:223], v206 offset:20512
	ds_read_b128 v[240:243], v206 offset:23072
	ds_read_b128 v[244:247], v206 offset:25632
	ds_read_b128 v[248:251], v206 offset:28192
	s_waitcnt lgkmcnt(9)
	v_mfma_f32_32x32x16_bf16 v[112:127], v[180:183], v[196:199], v[112:127]
	v_mfma_f32_32x32x16_bf16 v[96:111], v[180:183], v[228:231], v[96:111]
	s_waitcnt lgkmcnt(8)
	v_mfma_f32_32x32x16_bf16 v[80:95], v[184:187], v[196:199], v[80:95]
	v_mfma_f32_32x32x16_bf16 v[64:79], v[184:187], v[228:231], v[64:79]
	s_waitcnt vmcnt(0)
	ds_write_b128 v202, v[128:131] offset:0
	ds_write_b128 v202, v[132:135] offset:5120
	ds_write_b128 v202, v[136:139] offset:10240
	ds_write_b128 v202, v[140:143] offset:15360
	ds_write_b128 v202, v[144:147] offset:40960
	ds_write_b128 v202, v[148:151] offset:46080
	s_waitcnt lgkmcnt(13)
	v_mfma_f32_32x32x16_bf16 v[48:63], v[188:191], v[196:199], v[48:63]
	v_mfma_f32_32x32x16_bf16 v[32:47], v[188:191], v[228:231], v[32:47]
	s_waitcnt lgkmcnt(12)
	v_mfma_f32_32x32x16_bf16 v[16:31], v[192:195], v[196:199], v[16:31]
	v_mfma_f32_32x32x16_bf16 v[0:15], v[192:195], v[228:231], v[0:15]
	s_waitcnt lgkmcnt(0)
	s_barrier
	ds_read_b128 v[196:199], v207 offset:40960
	ds_read_b128 v[228:231], v207 offset:43520
	ds_read_b128 v[180:183], v206 offset:0
	ds_read_b128 v[184:187], v206 offset:2560
	ds_read_b128 v[188:191], v206 offset:5120
	ds_read_b128 v[192:195], v206 offset:7680
	v_mfma_f32_32x32x16_bf16 v[112:127], v[220:223], v[232:235], v[112:127]
	v_mfma_f32_32x32x16_bf16 v[96:111], v[220:223], v[236:239], v[96:111]
	v_mfma_f32_32x32x16_bf16 v[80:95], v[240:243], v[232:235], v[80:95]
	v_mfma_f32_32x32x16_bf16 v[64:79], v[240:243], v[236:239], v[64:79]
	v_mfma_f32_32x32x16_bf16 v[48:63], v[244:247], v[232:235], v[48:63]
	v_mfma_f32_32x32x16_bf16 v[32:47], v[244:247], v[236:239], v[32:47]
	v_mfma_f32_32x32x16_bf16 v[16:31], v[248:251], v[232:235], v[16:31]
	v_mfma_f32_32x32x16_bf16 v[0:15], v[248:251], v[236:239], v[0:15]
	s_add_i32 s65, s65, -1
	s_cmp_lg_u32 s65, 0
	s_cbranch_scc1 .Lgemm_ipn_loop
; DI u32 pack2(float a, float b) { return (u32)f2bf(a) | ((u32)f2bf(b) << 16); }
; template <bool SWAP, int MI, class AF, class BF, class EF>
; DI void gemm_tile(const AF& af, const BF& bfn, const EF& ef, int m0, int n0, int K, char* smem) {
;     ...
; #pragma unroll
;   for (int i = 0; i < MI; ++i)
; #pragma unroll
;     for (int j = 0; j < 2; ++j)
; #pragma unroll
;       for (int rg = 0; rg < 4; ++rg) {
;         const int m = SWAP ? (m0 + wm * (MI * 32) + i * 32 + l32) : (m0 + wm * (MI * 32) + i * 32 + rg * 8 + h * 4);
;         const int n = SWAP ? (n0 + wn * 64 + j * 32 + rg * 8 + h * 4) : (n0 + wn * 64 + j * 32 + l32);
;         ef(m, n, acc[i][j][rg * 4 + 0], acc[i][j][rg * 4 + 1], acc[i][j][rg * 4 + 2], acc[i][j][rg * 4 + 3]);
;       }
; DI void phase_inproj(const Params& p, int l, int bid, int nblk, char* smem) {
;     ...
;   auto efN = [=](int m, int n, float v0, float v1, float v2, float v3) {
;     const int b = m / TPB, pos = m % TPB, np = n - 2304;
;     uint2 o = {pack2(v0, v1), pack2(v2, v3)};
;     *(uint2*)&PQT[((size_t)(b * 512 + np)) * TPB + pos] = o;
;   };
	s_waitcnt lgkmcnt(0)
	s_setprio 0
	s_waitcnt vmcnt(0)
	v_and_b32_e32 v128, 31, v218
	v_lshrrev_b32_e32 v129, 7, v218
	v_bfe_u32 v130, v218, 5, 1
	v_bfe_u32 v131, v218, 6, 1
	v_lshl_add_u32 v128, v131, 6, v128
	v_mul_u32_u24_e32 v128, 528, v128
	v_lshlrev_b32_e32 v129, 8, v129
	v_lshl_add_u32 v129, v130, 3, v129
	v_add_u32_e32 v128, v128, v129
	s_nop 7
	v_cvt_pk_bf16_f32 v112, v112, v113
	v_cvt_pk_bf16_f32 v113, v114, v115
	v_cvt_pk_bf16_f32 v116, v116, v117
	v_cvt_pk_bf16_f32 v117, v118, v119
	v_cvt_pk_bf16_f32 v120, v120, v121
	v_cvt_pk_bf16_f32 v121, v122, v123
	v_cvt_pk_bf16_f32 v124, v124, v125
	v_cvt_pk_bf16_f32 v125, v126, v127
	ds_write_b64 v128, v[112:113] offset:0
	ds_write_b64 v128, v[116:117] offset:16
	ds_write_b64 v128, v[120:121] offset:32
	ds_write_b64 v128, v[124:125] offset:48
	v_cvt_pk_bf16_f32 v96, v96, v97
	v_cvt_pk_bf16_f32 v97, v98, v99
	v_cvt_pk_bf16_f32 v100, v100, v101
	v_cvt_pk_bf16_f32 v101, v102, v103
	v_cvt_pk_bf16_f32 v104, v104, v105
	v_cvt_pk_bf16_f32 v105, v106, v107
	v_cvt_pk_bf16_f32 v108, v108, v109
	v_cvt_pk_bf16_f32 v109, v110, v111
	ds_write_b64 v128, v[96:97] offset:16896
	ds_write_b64 v128, v[100:101] offset:16912
	ds_write_b64 v128, v[104:105] offset:16928
	ds_write_b64 v128, v[108:109] offset:16944
	v_cvt_pk_bf16_f32 v80, v80, v81
	v_cvt_pk_bf16_f32 v81, v82, v83
	v_cvt_pk_bf16_f32 v84, v84, v85
	v_cvt_pk_bf16_f32 v85, v86, v87
	v_cvt_pk_bf16_f32 v88, v88, v89
	v_cvt_pk_bf16_f32 v89, v90, v91
	v_cvt_pk_bf16_f32 v92, v92, v93
	v_cvt_pk_bf16_f32 v93, v94, v95
	ds_write_b64 v128, v[80:81] offset:64
	ds_write_b64 v128, v[84:85] offset:80
	ds_write_b64 v128, v[88:89] offset:96
	ds_write_b64 v128, v[92:93] offset:112
	v_cvt_pk_bf16_f32 v64, v64, v65
	v_cvt_pk_bf16_f32 v65, v66, v67
	v_cvt_pk_bf16_f32 v68, v68, v69
	v_cvt_pk_bf16_f32 v69, v70, v71
	v_cvt_pk_bf16_f32 v72, v72, v73
	v_cvt_pk_bf16_f32 v73, v74, v75
	v_cvt_pk_bf16_f32 v76, v76, v77
	v_cvt_pk_bf16_f32 v77, v78, v79
	ds_write_b64 v128, v[64:65] offset:16960
	ds_write_b64 v128, v[68:69] offset:16976
	ds_write_b64 v128, v[72:73] offset:16992
	ds_write_b64 v128, v[76:77] offset:17008
	v_cvt_pk_bf16_f32 v48, v48, v49
	v_cvt_pk_bf16_f32 v49, v50, v51
	v_cvt_pk_bf16_f32 v52, v52, v53
	v_cvt_pk_bf16_f32 v53, v54, v55
	v_cvt_pk_bf16_f32 v56, v56, v57
	v_cvt_pk_bf16_f32 v57, v58, v59
	v_cvt_pk_bf16_f32 v60, v60, v61
	v_cvt_pk_bf16_f32 v61, v62, v63
	ds_write_b64 v128, v[48:49] offset:128
	ds_write_b64 v128, v[52:53] offset:144
	ds_write_b64 v128, v[56:57] offset:160
	ds_write_b64 v128, v[60:61] offset:176
	v_cvt_pk_bf16_f32 v32, v32, v33
	v_cvt_pk_bf16_f32 v33, v34, v35
	v_cvt_pk_bf16_f32 v36, v36, v37
	v_cvt_pk_bf16_f32 v37, v38, v39
	v_cvt_pk_bf16_f32 v40, v40, v41
	v_cvt_pk_bf16_f32 v41, v42, v43
	v_cvt_pk_bf16_f32 v44, v44, v45
	v_cvt_pk_bf16_f32 v45, v46, v47
	ds_write_b64 v128, v[32:33] offset:17024
	ds_write_b64 v128, v[36:37] offset:17040
	ds_write_b64 v128, v[40:41] offset:17056
	ds_write_b64 v128, v[44:45] offset:17072
	v_cvt_pk_bf16_f32 v16, v16, v17
	v_cvt_pk_bf16_f32 v17, v18, v19
	v_cvt_pk_bf16_f32 v20, v20, v21
	v_cvt_pk_bf16_f32 v21, v22, v23
	v_cvt_pk_bf16_f32 v24, v24, v25
	v_cvt_pk_bf16_f32 v25, v26, v27
	v_cvt_pk_bf16_f32 v28, v28, v29
	v_cvt_pk_bf16_f32 v29, v30, v31
	ds_write_b64 v128, v[16:17] offset:192
	ds_write_b64 v128, v[20:21] offset:208
	ds_write_b64 v128, v[24:25] offset:224
	ds_write_b64 v128, v[28:29] offset:240
	v_cvt_pk_bf16_f32 v0, v0, v1
	v_cvt_pk_bf16_f32 v1, v2, v3
	v_cvt_pk_bf16_f32 v4, v4, v5
	v_cvt_pk_bf16_f32 v5, v6, v7
	v_cvt_pk_bf16_f32 v8, v8, v9
	v_cvt_pk_bf16_f32 v9, v10, v11
	v_cvt_pk_bf16_f32 v12, v12, v13
	v_cvt_pk_bf16_f32 v13, v14, v15
	ds_write_b64 v128, v[0:1] offset:17088
	ds_write_b64 v128, v[4:5] offset:17104
	ds_write_b64 v128, v[8:9] offset:17120
	ds_write_b64 v128, v[12:13] offset:17136
	s_mul_hi_u32 s36, s73, 0x38e38e39
	s_lshr_b32 s36, s36, 9
	s_mul_i32 s37, s36, 0x900
	s_sub_u32 s37, s73, s37
	s_lshl_b32 s36, s36, 9
	s_add_i32 s36, s36, s72
	s_add_i32 s36, s36, 0xfffff700
	s_mul_i32 s36, s36, 0x900
	s_add_i32 s36, s36, s37
	s_lshl_b32 s16, s36, 1
	s_add_u32 s16, s16, 0x13200000
	s_add_u32 s16, s96, s16
	s_addc_u32 s17, s97, 0
	s_movk_i32 s38, 0x1200
	s_mov_b32 s39, 0x9000
	v_lshrrev_b32_e32 v129, 5, v218
	v_and_b32_e32 v130, 31, v218
	v_mul_u32_u24_e32 v131, 528, v129
	v_mul_lo_u32 v132, v129, s38
	v_lshl_add_u32 v131, v130, 4, v131
	v_lshl_add_u32 v132, v130, 4, v132
	s_waitcnt lgkmcnt(0)
	s_barrier
	ds_read_b128 v[0:3], v131 offset:0
	ds_read_b128 v[4:7], v131 offset:4224
	ds_read_b128 v[8:11], v131 offset:8448
	ds_read_b128 v[12:15], v131 offset:12672
	ds_read_b128 v[16:19], v131 offset:16896
	ds_read_b128 v[20:23], v131 offset:21120
	ds_read_b128 v[24:27], v131 offset:25344
	ds_read_b128 v[28:31], v131 offset:29568
	ds_read_b128 v[32:35], v131 offset:33792
	ds_read_b128 v[36:39], v131 offset:38016
	ds_read_b128 v[40:43], v131 offset:42240
	ds_read_b128 v[44:47], v131 offset:46464
	ds_read_b128 v[48:51], v131 offset:50688
	ds_read_b128 v[52:55], v131 offset:54912
	ds_read_b128 v[56:59], v131 offset:59136
	ds_read_b128 v[60:63], v131 offset:63360
	s_waitcnt lgkmcnt(15)
	global_store_dwordx4 v132, v[0:3], s[16:17]
	s_add_u32 s16, s16, s39
	s_addc_u32 s17, s17, 0
	s_waitcnt lgkmcnt(14)
	global_store_dwordx4 v132, v[4:7], s[16:17]
	s_add_u32 s16, s16, s39
	s_addc_u32 s17, s17, 0
	s_waitcnt lgkmcnt(13)
	global_store_dwordx4 v132, v[8:11], s[16:17]
	s_add_u32 s16, s16, s39
	s_addc_u32 s17, s17, 0
	s_waitcnt lgkmcnt(12)
	global_store_dwordx4 v132, v[12:15], s[16:17]
	s_add_u32 s16, s16, s39
	s_addc_u32 s17, s17, 0
	s_waitcnt lgkmcnt(11)
	global_store_dwordx4 v132, v[16:19], s[16:17]
	s_add_u32 s16, s16, s39
	s_addc_u32 s17, s17, 0
	s_waitcnt lgkmcnt(10)
	global_store_dwordx4 v132, v[20:23], s[16:17]
	s_add_u32 s16, s16, s39
	s_addc_u32 s17, s17, 0
	s_waitcnt lgkmcnt(9)
	global_store_dwordx4 v132, v[24:27], s[16:17]
	s_add_u32 s16, s16, s39
	s_addc_u32 s17, s17, 0
	s_waitcnt lgkmcnt(8)
	global_store_dwordx4 v132, v[28:31], s[16:17]
	s_add_u32 s16, s16, s39
	s_addc_u32 s17, s17, 0
	s_waitcnt lgkmcnt(7)
	global_store_dwordx4 v132, v[32:35], s[16:17]
	s_add_u32 s16, s16, s39
	s_addc_u32 s17, s17, 0
	s_waitcnt lgkmcnt(6)
	global_store_dwordx4 v132, v[36:39], s[16:17]
	s_add_u32 s16, s16, s39
	s_addc_u32 s17, s17, 0
	s_waitcnt lgkmcnt(5)
	global_store_dwordx4 v132, v[40:43], s[16:17]
	s_add_u32 s16, s16, s39
	s_addc_u32 s17, s17, 0
	s_waitcnt lgkmcnt(4)
	global_store_dwordx4 v132, v[44:47], s[16:17]
	s_add_u32 s16, s16, s39
	s_addc_u32 s17, s17, 0
	s_waitcnt lgkmcnt(3)
	global_store_dwordx4 v132, v[48:51], s[16:17]
	s_add_u32 s16, s16, s39
	s_addc_u32 s17, s17, 0
	s_waitcnt lgkmcnt(2)
	global_store_dwordx4 v132, v[52:55], s[16:17]
	s_add_u32 s16, s16, s39
	s_addc_u32 s17, s17, 0
	s_waitcnt lgkmcnt(1)
	global_store_dwordx4 v132, v[56:59], s[16:17]
	s_add_u32 s16, s16, s39
	s_addc_u32 s17, s17, 0
	s_waitcnt lgkmcnt(0)
	global_store_dwordx4 v132, v[60:63], s[16:17]
	s_barrier
	s_branch .LBB0_416

; DI int TID() { int t = threadIdx.x; asm volatile("" : "+v"(t)); return t; }
; template <bool SWAP, int MI, class AF, class BF, class EF>
; DI void gemm_tile(const AF& af, const BF& bfn, const EF& ef, int m0, int n0, int K, char* smem) {
;   constexpr int AROWS = MI * 64;
;   u16* As = (u16*)smem;
;   u16* Bs = As + 2 * AROWS * 40;
;   const int tid = TID(), lane = tid & 63, w = tid >> 6;
;   const int wm = w >> 1, wn = w & 1, l32 = lane & 31, h = lane >> 5;
;   const int lrow = (tid >> 6) * 16 + ((tid >> 5) & 1) * 8 + ((tid >> 2) & 1) * 4 + ((tid >> 3) & 3), lk = (tid & 3) * 8;
;   f32x16 acc[MI][2];
; #pragma unroll
;   for (int i = 0; i < MI; ++i)
; #pragma unroll
;     for (int j = 0; j < 2; ++j)
; #pragma unroll
;       for (int r = 0; r < 16; ++r) acc[i][j][r] = 0.f;
;   u32x4 ra[MI], rb[2];
;   const int nk = K >> 5;
; #pragma unroll
;   for (int i = 0; i < MI; ++i) ra[i] = *(const u32x4*)af(m0 + lrow + 64 * i, lk);
; #pragma unroll
;   for (int i = 0; i < 2; ++i) rb[i] = *(const u32x4*)bfn(n0 + lrow + 64 * i, lk);
; #pragma unroll
;   for (int i = 0; i < MI; ++i) *(u32x4*)&As[(lrow + 64 * i) * 40 + lk] = ra[i];
; #pragma unroll
;   for (int i = 0; i < 2; ++i) *(u32x4*)&Bs[(lrow + 64 * i) * 40 + lk] = rb[i];
;   {
;     const int k1 = (nk > 1) ? 32 + lk : lk;
; #pragma unroll
;     for (int i = 0; i < MI; ++i) ra[i] = *(const u32x4*)af(m0 + lrow + 64 * i, k1);
; #pragma unroll
;     for (int i = 0; i < 2; ++i) rb[i] = *(const u32x4*)bfn(n0 + lrow + 64 * i, k1);
;   }
;   __syncthreads();
; DI void phase_q(const Params& p, int l, int bid, int nblk, char* smem) {
;     ...
;   const int ntile = (l == 1 ? NB * 8 : ROWS / 256) * 16;
;   const int vb = (nblk % 8 == 0) ? (bid & 7) * (nblk >> 3) + (bid >> 3) : bid;
;   for (int t = vb; t < ntile; t += nblk) {
;     const int mi = t >> 4, nt = t & 15;
;     const int mt = (l == 1) ? (mi >> 3) * 9 + (mi & 7) + 1 : mi;
;     gemm_tile<true, 4>(af, bfn, ef, mt * 256, nt * 128, 1024, smem);
.LBB0_1390:
	s_lshl_b32 s78, s35, 8
	s_and_b32 s79, s34, 15
	s_lshl_b32 s79, s79, 7
	v_readlane_b32 s66, v253, 0
	s_nop 0
	s_lshr_b32 s66, s66, 8
	s_cmp_lg_u32 s66, 0
	s_cbranch_scc0 .Lgemm_q_np
	s_setprio 1
.Lgemm_q_np:
	v_lshrrev_b32_e32 v128, 6, v218
	v_bfe_u32 v129, v218, 5, 1
	v_bfe_u32 v130, v218, 2, 1
	v_bfe_u32 v131, v218, 3, 2
	v_lshlrev_b32_e32 v132, 4, v128
	v_lshl_add_u32 v132, v129, 3, v132
	v_lshl_add_u32 v132, v130, 2, v132
	v_add_u32_e32 v132, v132, v131
	v_and_b32_e32 v133, 3, v218
	v_lshlrev_b32_e32 v133, 4, v133
	v_lshl_add_u32 v200, v132, 11, v133
	v_mul_u32_u24_e32 v134, 80, v132
	v_add_u32_e32 v202, v134, v133
	v_and_b32_e32 v135, 31, v218
	v_lshrrev_b32_e32 v136, 7, v218
	v_bfe_u32 v137, v218, 6, 1
	v_lshl_add_u32 v136, v136, 7, v135
	v_lshl_add_u32 v137, v137, 6, v135
	v_mul_u32_u24_e32 v136, 80, v136
	v_mul_u32_u24_e32 v137, 80, v137
	v_lshl_add_u32 v206, v129, 4, v136
	v_lshl_add_u32 v207, v129, 4, v137
	s_add_i32 s66, s78, 0
	s_lshl_b32 s66, s66, 11
	s_add_u32 s36, s6, s66
	s_addc_u32 s37, s7, 0
	s_add_i32 s66, s78, 64
	s_lshl_b32 s66, s66, 11
	s_add_u32 s38, s6, s66
	s_addc_u32 s39, s7, 0
	s_add_i32 s66, s78, 128
	s_lshl_b32 s66, s66, 11
	s_add_u32 s42, s6, s66
	s_addc_u32 s43, s7, 0
	s_add_i32 s66, s78, 192
	s_lshl_b32 s66, s66, 11
	s_add_u32 s46, s6, s66
	s_addc_u32 s47, s7, 0
	s_add_i32 s66, s79, 0
	s_lshl_b32 s66, s66, 11
	s_add_u32 s48, s0, s66
	s_addc_u32 s49, s1, 0
	s_add_i32 s66, s79, 64
	s_lshl_b32 s66, s66, 11
	s_add_u32 s50, s0, s66
	s_addc_u32 s51, s1, 0
	v_mov_b64_e32 v[0:1], 0
	v_mov_b64_e32 v[2:3], 0
	v_mov_b64_e32 v[4:5], 0
	v_mov_b64_e32 v[6:7], 0
	v_mov_b64_e32 v[8:9], 0
	v_mov_b64_e32 v[10:11], 0
	v_mov_b64_e32 v[12:13], 0
	v_mov_b64_e32 v[14:15], 0
	v_mov_b64_e32 v[16:17], 0
	v_mov_b64_e32 v[18:19], 0
	v_mov_b64_e32 v[20:21], 0
	v_mov_b64_e32 v[22:23], 0
	v_mov_b64_e32 v[24:25], 0
	v_mov_b64_e32 v[26:27], 0
	v_mov_b64_e32 v[28:29], 0
	v_mov_b64_e32 v[30:31], 0
	v_mov_b64_e32 v[32:33], 0
	v_mov_b64_e32 v[34:35], 0
	v_mov_b64_e32 v[36:37], 0
	v_mov_b64_e32 v[38:39], 0
	v_mov_b64_e32 v[40:41], 0
	v_mov_b64_e32 v[42:43], 0
	v_mov_b64_e32 v[44:45], 0
	v_mov_b64_e32 v[46:47], 0
	v_mov_b64_e32 v[48:49], 0
	v_mov_b64_e32 v[50:51], 0
	v_mov_b64_e32 v[52:53], 0
	v_mov_b64_e32 v[54:55], 0
	v_mov_b64_e32 v[56:57], 0
	v_mov_b64_e32 v[58:59], 0
	v_mov_b64_e32 v[60:61], 0
	v_mov_b64_e32 v[62:63], 0
	v_mov_b64_e32 v[64:65], 0
	v_mov_b64_e32 v[66:67], 0
	v_mov_b64_e32 v[68:69], 0
	v_mov_b64_e32 v[70:71], 0
	v_mov_b64_e32 v[72:73], 0
	v_mov_b64_e32 v[74:75], 0
	v_mov_b64_e32 v[76:77], 0
	v_mov_b64_e32 v[78:79], 0
	v_mov_b64_e32 v[80:81], 0
	v_mov_b64_e32 v[82:83], 0
	v_mov_b64_e32 v[84:85], 0
	v_mov_b64_e32 v[86:87], 0
	v_mov_b64_e32 v[88:89], 0
	v_mov_b64_e32 v[90:91], 0
	v_mov_b64_e32 v[92:93], 0
	v_mov_b64_e32 v[94:95], 0
	v_mov_b64_e32 v[96:97], 0
	v_mov_b64_e32 v[98:99], 0
	v_mov_b64_e32 v[100:101], 0
	v_mov_b64_e32 v[102:103], 0
	v_mov_b64_e32 v[104:105], 0
	v_mov_b64_e32 v[106:107], 0
	v_mov_b64_e32 v[108:109], 0
	v_mov_b64_e32 v[110:111], 0
	v_mov_b64_e32 v[112:113], 0
	v_mov_b64_e32 v[114:115], 0
	v_mov_b64_e32 v[116:117], 0
	v_mov_b64_e32 v[118:119], 0
	v_mov_b64_e32 v[120:121], 0
	v_mov_b64_e32 v[122:123], 0
	v_mov_b64_e32 v[124:125], 0
	v_mov_b64_e32 v[126:127], 0
	s_mov_b32 s64, 0
	v_add_u32_e32 v201, s64, v200
	global_load_dwordx4 v[128:131], v201, s[36:37]
	global_load_dwordx4 v[152:155], v201, s[36:37] offset:64
	global_load_dwordx4 v[132:135], v201, s[38:39]
	global_load_dwordx4 v[156:159], v201, s[38:39] offset:64
	global_load_dwordx4 v[136:139], v201, s[42:43]
	global_load_dwordx4 v[160:163], v201, s[42:43] offset:64
	global_load_dwordx4 v[140:143], v201, s[46:47]
	global_load_dwordx4 v[164:167], v201, s[46:47] offset:64
	global_load_dwordx4 v[144:147], v201, s[48:49]
	global_load_dwordx4 v[168:171], v201, s[48:49] offset:64
	global_load_dwordx4 v[148:151], v201, s[50:51]
	global_load_dwordx4 v[176:179], v201, s[50:51] offset:64
	s_add_i32 s64, s64, 0x80
	s_movk_i32 s65, 16
	s_waitcnt vmcnt(0)
	ds_write_b128 v202, v[128:131] offset:0
	ds_write_b128 v202, v[132:135] offset:5120
	ds_write_b128 v202, v[136:139] offset:10240
	ds_write_b128 v202, v[140:143] offset:15360
	ds_write_b128 v202, v[144:147] offset:40960
	ds_write_b128 v202, v[148:151] offset:46080
	s_waitcnt lgkmcnt(0)
	s_barrier
	ds_read_b128 v[196:199], v207 offset:40960
	ds_read_b128 v[228:231], v207 offset:43520
	ds_read_b128 v[180:183], v206 offset:0
	ds_read_b128 v[184:187], v206 offset:2560
	ds_read_b128 v[188:191], v206 offset:5120
	ds_read_b128 v[192:195], v206 offset:7680
; template <bool SWAP, int MI, class AF, class BF, class EF>
; DI void gemm_tile(const AF& af, const BF& bfn, const EF& ef, int m0, int n0, int K, char* smem) {
;     ...
;   for (int kt = 0; kt < nk; ++kt) {
;     const int cur = kt & 1;
;     const u16* Ab = As + cur * AROWS * 40;
;     const u16* Bb = Bs + cur * 128 * 40;
; #pragma unroll
;     for (int ks = 0; ks < 2; ++ks) {
;       bf16x8 a[MI], b[2];
; #pragma unroll
;       for (int i = 0; i < MI; ++i) a[i] = *(const bf16x8*)&Ab[(wm * (MI * 32) + i * 32 + l32) * 40 + ks * 16 + h * 8];
; #pragma unroll
;       for (int i = 0; i < 2; ++i) b[i] = *(const bf16x8*)&Bb[(wn * 64 + i * 32 + l32) * 40 + ks * 16 + h * 8];
; #pragma unroll
;       for (int i = 0; i < MI; ++i)
; #pragma unroll
;         for (int j = 0; j < 2; ++j)
;           acc[i][j] = SWAP ? __builtin_amdgcn_mfma_f32_32x32x16_bf16(b[j], a[i], acc[i][j], 0, 0, 0)
;                            : __builtin_amdgcn_mfma_f32_32x32x16_bf16(a[i], b[j], acc[i][j], 0, 0, 0);
;     }
;     {
;       u16* An = As + (cur ^ 1) * AROWS * 40;
;       u16* Bn = Bs + (cur ^ 1) * 128 * 40;
; #pragma unroll
;       for (int i = 0; i < MI; ++i) *(u32x4*)&An[(lrow + 64 * i) * 40 + lk] = ra[i];
; #pragma unroll
;       for (int i = 0; i < 2; ++i) *(u32x4*)&Bn[(lrow + 64 * i) * 40 + lk] = rb[i];
;       const int kn = (kt + 2 < nk) ? kt + 2 : nk - 1;
;       const int k0 = kn * 32 + lk;
; #pragma unroll
;       for (int i = 0; i < MI; ++i) ra[i] = *(const u32x4*)af(m0 + lrow + 64 * i, k0);
; #pragma unroll
;       for (int i = 0; i < 2; ++i) rb[i] = *(const u32x4*)bfn(n0 + lrow + 64 * i, k0);
;     }
;     __syncthreads();
;   }
.Lgemm_q_loop:
	ds_read_b128 v[232:235], v207 offset:40992
	ds_read_b128 v[236:239], v207 offset:43552
	ds_read_b128 v[220:223], v206 offset:32
	ds_read_b128 v[240:243], v206 offset:2592
	ds_read_b128 v[244:247], v206 offset:5152
	ds_read_b128 v[248:251], v206 offset:7712
	s_waitcnt lgkmcnt(9)
	v_mfma_f32_32x32x16_bf16 v[112:127], v[196:199], v[180:183], v[112:127]
	v_mfma_f32_32x32x16_bf16 v[96:111], v[228:231], v[180:183], v[96:111]
	s_waitcnt lgkmcnt(8)
	v_mfma_f32_32x32x16_bf16 v[80:95], v[196:199], v[184:187], v[80:95]
	v_mfma_f32_32x32x16_bf16 v[64:79], v[228:231], v[184:187], v[64:79]
	ds_write_b128 v202, v[152:155] offset:20480
	ds_write_b128 v202, v[156:159] offset:25600
	ds_write_b128 v202, v[160:163] offset:30720
	ds_write_b128 v202, v[164:167] offset:35840
	ds_write_b128 v202, v[168:171] offset:51200
	ds_write_b128 v202, v[176:179] offset:56320
	v_add_u32_e32 v201, s64, v200
	global_load_dwordx4 v[128:131], v201, s[36:37]
	global_load_dwordx4 v[152:155], v201, s[36:37] offset:64
	global_load_dwordx4 v[132:135], v201, s[38:39]
	global_load_dwordx4 v[156:159], v201, s[38:39] offset:64
	global_load_dwordx4 v[136:139], v201, s[42:43]
	global_load_dwordx4 v[160:163], v201, s[42:43] offset:64
	global_load_dwordx4 v[140:143], v201, s[46:47]
	global_load_dwordx4 v[164:167], v201, s[46:47] offset:64
	global_load_dwordx4 v[144:147], v201, s[48:49]
	global_load_dwordx4 v[168:171], v201, s[48:49] offset:64
	global_load_dwordx4 v[148:151], v201, s[50:51]
	global_load_dwordx4 v[176:179], v201, s[50:51] offset:64
	s_add_i32 s64, s64, 0x80
	s_min_u32 s64, s64, 0x780
	s_waitcnt lgkmcnt(13)
	v_mfma_f32_32x32x16_bf16 v[48:63], v[196:199], v[188:191], v[48:63]
	v_mfma_f32_32x32x16_bf16 v[32:47], v[228:231], v[188:191], v[32:47]
	s_waitcnt lgkmcnt(12)
	v_mfma_f32_32x32x16_bf16 v[16:31], v[196:199], v[192:195], v[16:31]
	v_mfma_f32_32x32x16_bf16 v[0:15], v[228:231], v[192:195], v[0:15]
	s_waitcnt lgkmcnt(0)
	s_barrier
	ds_read_b128 v[196:199], v207 offset:51200
	ds_read_b128 v[228:231], v207 offset:53760
	ds_read_b128 v[180:183], v206 offset:20480
	ds_read_b128 v[184:187], v206 offset:23040
	ds_read_b128 v[188:191], v206 offset:25600
	ds_read_b128 v[192:195], v206 offset:28160
	v_mfma_f32_32x32x16_bf16 v[112:127], v[232:235], v[220:223], v[112:127]
	v_mfma_f32_32x32x16_bf16 v[96:111], v[236:239], v[220:223], v[96:111]
	v_mfma_f32_32x32x16_bf16 v[80:95], v[232:235], v[240:243], v[80:95]
	v_mfma_f32_32x32x16_bf16 v[64:79], v[236:239], v[240:243], v[64:79]
	v_mfma_f32_32x32x16_bf16 v[48:63], v[232:235], v[244:247], v[48:63]
	v_mfma_f32_32x32x16_bf16 v[32:47], v[236:239], v[244:247], v[32:47]
	v_mfma_f32_32x32x16_bf16 v[16:31], v[232:235], v[248:251], v[16:31]
	v_mfma_f32_32x32x16_bf16 v[0:15], v[236:239], v[248:251], v[0:15]
	ds_read_b128 v[232:235], v207 offset:51232
	ds_read_b128 v[236:239], v207 offset:53792
	ds_read_b128 v[220:223], v206 offset:20512
	ds_read_b128 v[240:243], v206 offset:23072
	ds_read_b128 v[244:247], v206 offset:25632
	ds_read_b128 v[248:251], v206 offset:28192
	s_waitcnt lgkmcnt(9)
	v_mfma_f32_32x32x16_bf16 v[112:127], v[196:199], v[180:183], v[112:127]
	v_mfma_f32_32x32x16_bf16 v[96:111], v[228:231], v[180:183], v[96:111]
	s_waitcnt lgkmcnt(8)
	v_mfma_f32_32x32x16_bf16 v[80:95], v[196:199], v[184:187], v[80:95]
	v_mfma_f32_32x32x16_bf16 v[64:79], v[228:231], v[184:187], v[64:79]
	s_waitcnt vmcnt(0)
	ds_write_b128 v202, v[128:131] offset:0
	ds_write_b128 v202, v[132:135] offset:5120
	ds_write_b128 v202, v[136:139] offset:10240
	ds_write_b128 v202, v[140:143] offset:15360
	ds_write_b128 v202, v[144:147] offset:40960
	ds_write_b128 v202, v[148:151] offset:46080
	s_waitcnt lgkmcnt(13)
	v_mfma_f32_32x32x16_bf16 v[48:63], v[196:199], v[188:191], v[48:63]
	v_mfma_f32_32x32x16_bf16 v[32:47], v[228:231], v[188:191], v[32:47]
	s_waitcnt lgkmcnt(12)
	v_mfma_f32_32x32x16_bf16 v[16:31], v[196:199], v[192:195], v[16:31]
	v_mfma_f32_32x32x16_bf16 v[0:15], v[228:231], v[192:195], v[0:15]
	s_waitcnt lgkmcnt(0)
	s_barrier
	ds_read_b128 v[196:199], v207 offset:40960
	ds_read_b128 v[228:231], v207 offset:43520
	ds_read_b128 v[180:183], v206 offset:0
	ds_read_b128 v[184:187], v206 offset:2560
	ds_read_b128 v[188:191], v206 offset:5120
	ds_read_b128 v[192:195], v206 offset:7680
	v_mfma_f32_32x32x16_bf16 v[112:127], v[232:235], v[220:223], v[112:127]
	v_mfma_f32_32x32x16_bf16 v[96:111], v[236:239], v[220:223], v[96:111]
	v_mfma_f32_32x32x16_bf16 v[80:95], v[232:235], v[240:243], v[80:95]
	v_mfma_f32_32x32x16_bf16 v[64:79], v[236:239], v[240:243], v[64:79]
	v_mfma_f32_32x32x16_bf16 v[48:63], v[232:235], v[244:247], v[48:63]
	v_mfma_f32_32x32x16_bf16 v[32:47], v[236:239], v[244:247], v[32:47]
	v_mfma_f32_32x32x16_bf16 v[16:31], v[232:235], v[248:251], v[16:31]
	v_mfma_f32_32x32x16_bf16 v[0:15], v[236:239], v[248:251], v[0:15]
	s_add_i32 s65, s65, -1
	s_cmp_lg_u32 s65, 0
	s_cbranch_scc1 .Lgemm_q_loop
; DI u32 pack2(float a, float b) { return (u32)f2bf(a) | ((u32)f2bf(b) << 16); }
; template <bool SWAP, int MI, class AF, class BF, class EF>
; DI void gemm_tile(const AF& af, const BF& bfn, const EF& ef, int m0, int n0, int K, char* smem) {
;     ...
; #pragma unroll
;   for (int i = 0; i < MI; ++i)
; #pragma unroll
;     for (int j = 0; j < 2; ++j)
; #pragma unroll
;       for (int rg = 0; rg < 4; ++rg) {
;         const int m = SWAP ? (m0 + wm * (MI * 32) + i * 32 + l32) : (m0 + wm * (MI * 32) + i * 32 + rg * 8 + h * 4);
;         const int n = SWAP ? (n0 + wn * 64 + j * 32 + rg * 8 + h * 4) : (n0 + wn * 64 + j * 32 + l32);
;         ef(m, n, acc[i][j][rg * 4 + 0], acc[i][j][rg * 4 + 1], acc[i][j][rg * 4 + 2], acc[i][j][rg * 4 + 3]);
;       }
; DI void phase_q(const Params& p, int l, int bid, int nblk, char* smem) {
;     ...
;   auto ef = [=](int m, int n, float v0, float v1, float v2, float v3) {
;     const uint2 o = {pack2(v0, v1), pack2(v2, v3)};
;     *(uint2*)&Q[(size_t)m * 2048 + n] = o;
;   };
;   const int ntile = (l == 1 ? NB * 8 : ROWS / 256) * 16;
;   const int vb = (nblk % 8 == 0) ? (bid & 7) * (nblk >> 3) + (bid >> 3) : bid;
;   for (int t = vb; t < ntile; t += nblk) {
;     const int mi = t >> 4, nt = t & 15;
;     const int mt = (l == 1) ? (mi >> 3) * 9 + (mi & 7) + 1 : mi;
;     gemm_tile<true, 4>(af, bfn, ef, mt * 256, nt * 128, 1024, smem);
	s_waitcnt lgkmcnt(0)
	s_setprio 0
	s_waitcnt vmcnt(0)
	v_and_b32_e32 v128, 31, v218
	v_lshrrev_b32_e32 v129, 7, v218
	v_bfe_u32 v130, v218, 5, 1
	v_bfe_u32 v131, v218, 6, 1
	v_lshl_add_u32 v128, v129, 7, v128
	v_mul_u32_u24_e32 v128, 272, v128
	v_lshlrev_b32_e32 v131, 7, v131
	v_lshl_add_u32 v131, v130, 3, v131
	v_add_u32_e32 v128, v128, v131
	s_nop 7
	v_cvt_pk_bf16_f32 v112, v112, v113
	v_cvt_pk_bf16_f32 v113, v114, v115
	v_cvt_pk_bf16_f32 v116, v116, v117
	v_cvt_pk_bf16_f32 v117, v118, v119
	v_cvt_pk_bf16_f32 v120, v120, v121
	v_cvt_pk_bf16_f32 v121, v122, v123
	v_cvt_pk_bf16_f32 v124, v124, v125
	v_cvt_pk_bf16_f32 v125, v126, v127
	ds_write_b64 v128, v[112:113] offset:0
	ds_write_b64 v128, v[116:117] offset:16
	ds_write_b64 v128, v[120:121] offset:32
	ds_write_b64 v128, v[124:125] offset:48
	v_cvt_pk_bf16_f32 v96, v96, v97
	v_cvt_pk_bf16_f32 v97, v98, v99
	v_cvt_pk_bf16_f32 v100, v100, v101
	v_cvt_pk_bf16_f32 v101, v102, v103
	v_cvt_pk_bf16_f32 v104, v104, v105
	v_cvt_pk_bf16_f32 v105, v106, v107
	v_cvt_pk_bf16_f32 v108, v108, v109
	v_cvt_pk_bf16_f32 v109, v110, v111
	ds_write_b64 v128, v[96:97] offset:64
	ds_write_b64 v128, v[100:101] offset:80
	ds_write_b64 v128, v[104:105] offset:96
	ds_write_b64 v128, v[108:109] offset:112
	v_cvt_pk_bf16_f32 v80, v80, v81
	v_cvt_pk_bf16_f32 v81, v82, v83
	v_cvt_pk_bf16_f32 v84, v84, v85
	v_cvt_pk_bf16_f32 v85, v86, v87
	v_cvt_pk_bf16_f32 v88, v88, v89
	v_cvt_pk_bf16_f32 v89, v90, v91
	v_cvt_pk_bf16_f32 v92, v92, v93
	v_cvt_pk_bf16_f32 v93, v94, v95
	ds_write_b64 v128, v[80:81] offset:8704
	ds_write_b64 v128, v[84:85] offset:8720
	ds_write_b64 v128, v[88:89] offset:8736
	ds_write_b64 v128, v[92:93] offset:8752
	v_cvt_pk_bf16_f32 v64, v64, v65
	v_cvt_pk_bf16_f32 v65, v66, v67
	v_cvt_pk_bf16_f32 v68, v68, v69
	v_cvt_pk_bf16_f32 v69, v70, v71
	v_cvt_pk_bf16_f32 v72, v72, v73
	v_cvt_pk_bf16_f32 v73, v74, v75
	v_cvt_pk_bf16_f32 v76, v76, v77
	v_cvt_pk_bf16_f32 v77, v78, v79
	ds_write_b64 v128, v[64:65] offset:8768
	ds_write_b64 v128, v[68:69] offset:8784
	ds_write_b64 v128, v[72:73] offset:8800
	ds_write_b64 v128, v[76:77] offset:8816
	v_cvt_pk_bf16_f32 v48, v48, v49
	v_cvt_pk_bf16_f32 v49, v50, v51
	v_cvt_pk_bf16_f32 v52, v52, v53
	v_cvt_pk_bf16_f32 v53, v54, v55
	v_cvt_pk_bf16_f32 v56, v56, v57
	v_cvt_pk_bf16_f32 v57, v58, v59
	v_cvt_pk_bf16_f32 v60, v60, v61
	v_cvt_pk_bf16_f32 v61, v62, v63
	ds_write_b64 v128, v[48:49] offset:17408
	ds_write_b64 v128, v[52:53] offset:17424
	ds_write_b64 v128, v[56:57] offset:17440
	ds_write_b64 v128, v[60:61] offset:17456
	v_cvt_pk_bf16_f32 v32, v32, v33
	v_cvt_pk_bf16_f32 v33, v34, v35
	v_cvt_pk_bf16_f32 v36, v36, v37
	v_cvt_pk_bf16_f32 v37, v38, v39
	v_cvt_pk_bf16_f32 v40, v40, v41
	v_cvt_pk_bf16_f32 v41, v42, v43
	v_cvt_pk_bf16_f32 v44, v44, v45
	v_cvt_pk_bf16_f32 v45, v46, v47
	ds_write_b64 v128, v[32:33] offset:17472
	ds_write_b64 v128, v[36:37] offset:17488
	ds_write_b64 v128, v[40:41] offset:17504
	ds_write_b64 v128, v[44:45] offset:17520
	v_cvt_pk_bf16_f32 v16, v16, v17
	v_cvt_pk_bf16_f32 v17, v18, v19
	v_cvt_pk_bf16_f32 v20, v20, v21
	v_cvt_pk_bf16_f32 v21, v22, v23
	v_cvt_pk_bf16_f32 v24, v24, v25
	v_cvt_pk_bf16_f32 v25, v26, v27
	v_cvt_pk_bf16_f32 v28, v28, v29
	v_cvt_pk_bf16_f32 v29, v30, v31
	ds_write_b64 v128, v[16:17] offset:26112
	ds_write_b64 v128, v[20:21] offset:26128
	ds_write_b64 v128, v[24:25] offset:26144
	ds_write_b64 v128, v[28:29] offset:26160
	v_cvt_pk_bf16_f32 v0, v0, v1
	v_cvt_pk_bf16_f32 v1, v2, v3
	v_cvt_pk_bf16_f32 v4, v4, v5
	v_cvt_pk_bf16_f32 v5, v6, v7
	v_cvt_pk_bf16_f32 v8, v8, v9
	v_cvt_pk_bf16_f32 v9, v10, v11
	v_cvt_pk_bf16_f32 v12, v12, v13
	v_cvt_pk_bf16_f32 v13, v14, v15
	ds_write_b64 v128, v[0:1] offset:26176
	ds_write_b64 v128, v[4:5] offset:26192
	ds_write_b64 v128, v[8:9] offset:26208
	ds_write_b64 v128, v[12:13] offset:26224
	s_lshl_b32 s16, s78, 12
	s_lshl_b32 s17, s79, 1
	s_add_u32 s16, s16, s17
	s_add_u32 s16, s96, s16
	s_addc_u32 s17, s97, 0
	s_movk_i32 s38, 0x1000
	s_mov_b32 s39, 0x10000
	v_lshrrev_b32_e32 v129, 4, v218
	v_and_b32_e32 v130, 15, v218
	v_mul_u32_u24_e32 v131, 272, v129
	v_mul_lo_u32 v132, v129, s38
	v_lshl_add_u32 v131, v130, 4, v131
	v_lshl_add_u32 v132, v130, 4, v132
	s_waitcnt lgkmcnt(0)
	s_barrier
	ds_read_b128 v[0:3], v131 offset:0
	ds_read_b128 v[4:7], v131 offset:4352
	ds_read_b128 v[8:11], v131 offset:8704
	ds_read_b128 v[12:15], v131 offset:13056
	ds_read_b128 v[16:19], v131 offset:17408
	ds_read_b128 v[20:23], v131 offset:21760
	ds_read_b128 v[24:27], v131 offset:26112
	ds_read_b128 v[28:31], v131 offset:30464
	ds_read_b128 v[32:35], v131 offset:34816
	ds_read_b128 v[36:39], v131 offset:39168
	ds_read_b128 v[40:43], v131 offset:43520
	ds_read_b128 v[44:47], v131 offset:47872
	ds_read_b128 v[48:51], v131 offset:52224
	ds_read_b128 v[52:55], v131 offset:56576
	ds_read_b128 v[56:59], v131 offset:60928
	ds_read_b128 v[60:63], v131 offset:65280
	s_waitcnt lgkmcnt(15)
	global_store_dwordx4 v132, v[0:3], s[16:17]
	s_add_u32 s16, s16, s39
	s_addc_u32 s17, s17, 0
	s_waitcnt lgkmcnt(14)
	global_store_dwordx4 v132, v[4:7], s[16:17]
	s_add_u32 s16, s16, s39
	s_addc_u32 s17, s17, 0
	s_waitcnt lgkmcnt(13)
	global_store_dwordx4 v132, v[8:11], s[16:17]
	s_add_u32 s16, s16, s39
	s_addc_u32 s17, s17, 0
	s_waitcnt lgkmcnt(12)
	global_store_dwordx4 v132, v[12:15], s[16:17]
	s_add_u32 s16, s16, s39
	s_addc_u32 s17, s17, 0
	s_waitcnt lgkmcnt(11)
	global_store_dwordx4 v132, v[16:19], s[16:17]
	s_add_u32 s16, s16, s39
	s_addc_u32 s17, s17, 0
	s_waitcnt lgkmcnt(10)
	global_store_dwordx4 v132, v[20:23], s[16:17]
	s_add_u32 s16, s16, s39
	s_addc_u32 s17, s17, 0
	s_waitcnt lgkmcnt(9)
	global_store_dwordx4 v132, v[24:27], s[16:17]
	s_add_u32 s16, s16, s39
	s_addc_u32 s17, s17, 0
	s_waitcnt lgkmcnt(8)
	global_store_dwordx4 v132, v[28:31], s[16:17]
	s_add_u32 s16, s16, s39
	s_addc_u32 s17, s17, 0
	s_waitcnt lgkmcnt(7)
	global_store_dwordx4 v132, v[32:35], s[16:17]
	s_add_u32 s16, s16, s39
	s_addc_u32 s17, s17, 0
	s_waitcnt lgkmcnt(6)
	global_store_dwordx4 v132, v[36:39], s[16:17]
	s_add_u32 s16, s16, s39
	s_addc_u32 s17, s17, 0
	s_waitcnt lgkmcnt(5)
	global_store_dwordx4 v132, v[40:43], s[16:17]
	s_add_u32 s16, s16, s39
	s_addc_u32 s17, s17, 0
	s_waitcnt lgkmcnt(4)
	global_store_dwordx4 v132, v[44:47], s[16:17]
	s_add_u32 s16, s16, s39
	s_addc_u32 s17, s17, 0
	s_waitcnt lgkmcnt(3)
	global_store_dwordx4 v132, v[48:51], s[16:17]
	s_add_u32 s16, s16, s39
	s_addc_u32 s17, s17, 0
	s_waitcnt lgkmcnt(2)
	global_store_dwordx4 v132, v[52:55], s[16:17]
	s_add_u32 s16, s16, s39
	s_addc_u32 s17, s17, 0
	s_waitcnt lgkmcnt(1)
	global_store_dwordx4 v132, v[56:59], s[16:17]
	s_add_u32 s16, s16, s39
	s_addc_u32 s17, s17, 0
	s_waitcnt lgkmcnt(0)
	global_store_dwordx4 v132, v[60:63], s[16:17]
	s_barrier
	s_add_i32 s34, s34, s54
	s_cmp_lt_i32 s34, s13
	s_cbranch_scc1 .LBB0_1387
